# P7 router column loop rewritten: 4 tokens' packed-FMA chains and DPP reductions interleaved (no hazard nops), all 16 weight loads of an iteration issued up front; arithmetic order unchanged
# speedup vs baseline: 1.0222x; 1.0222x over previous
; DEVI float wave_sum(float v) {
;   v = dpp_add_(v, 0);
;   v = dpp_add_(v, 1);
;   v = dpp_add_(v, 2);
;   v = dpp_add_(v, 3);
;   const int iv = __float_as_int(v);
;   const float r0 = __int_as_float(__builtin_amdgcn_readlane(iv, 0)), r1 = __int_as_float(__builtin_amdgcn_readlane(iv, 16));
;   const float r2 = __int_as_float(__builtin_amdgcn_readlane(iv, 32)), r3 = __int_as_float(__builtin_amdgcn_readlane(iv, 48));
;   return (r0 + r1) + (r2 + r3);
; DEVI void phase_p7(const int TIDX, const int BIDX, const int GDIM, KAP KA, unsigned char* WSB, float* OUTB, int l, unsigned char* smem) {
;     ...
; #pragma unroll 4
;       for (int c = 0; c < 36; ++c) {
;         float4 wv[4];
; #pragma unroll
;         for (int j = 0; j < 4; ++j) wv[j] = *(const float4*)(WR + c * 1024 + j * 256 + lane * 4);
; #pragma unroll
;         for (int t = 0; t < 4; ++t) {
;           float s = 0.f;
; #pragma unroll
;           for (int j = 0; j < 4; ++j) s += v[t][j].x * wv[j].x + v[t][j].y * wv[j].y + v[t][j].z * wv[j].z + v[t][j].w * wv[j].w;
;           s = wave_sum(s);
;           if (lane == c) mine[t] = s;
;         }
;       }
.LBB0_69:
	v_lshl_add_u64 v[80:81], v[42:43], 0, s[0:1]
	s_mov_b64 s[24:25], 0x2221000
	s_mov_b64 s[26:27], 0x2223000
	v_lshl_add_u64 v[90:91], v[80:81], 0, s[24:25]
	v_lshl_add_u64 v[92:93], v[80:81], 0, s[26:27]
	global_load_dwordx4 v[142:145], v[90:91], off offset:-4096
	global_load_dwordx4 v[146:149], v[90:91], off offset:-3072
	global_load_dwordx4 v[150:153], v[90:91], off offset:-2048
	global_load_dwordx4 v[154:157], v[90:91], off offset:-1024
	global_load_dwordx4 v[162:165], v[90:91], off
	global_load_dwordx4 v[166:169], v[90:91], off offset:1024
	global_load_dwordx4 v[170:173], v[90:91], off offset:2048
	global_load_dwordx4 v[174:177], v[90:91], off offset:3072
	global_load_dwordx4 v[178:181], v[92:93], off offset:-4096
	global_load_dwordx4 v[182:185], v[92:93], off offset:-3072
	global_load_dwordx4 v[186:189], v[92:93], off offset:-2048
	global_load_dwordx4 v[190:193], v[92:93], off offset:-1024
	global_load_dwordx4 v[196:199], v[92:93], off
	global_load_dwordx4 v[200:203], v[92:93], off offset:1024
	global_load_dwordx4 v[236:239], v[92:93], off offset:2048
	global_load_dwordx4 v[240:243], v[92:93], off offset:3072
	s_waitcnt vmcnt(14)
	v_mov_b32_e32 v252, v142
	v_mov_b32_e32 v253, v146
	v_mov_b32_e32 v146, v143
	v_mov_b32_e32 v158, v144
	v_mov_b32_e32 v159, v148
	v_mov_b32_e32 v148, v145
	v_pk_mul_f32 v[244:245], v[26:27], v[146:147]
	v_pk_mul_f32 v[246:247], v[56:57], v[146:147]
	v_pk_mul_f32 v[248:249], v[4:5], v[146:147]
	v_pk_mul_f32 v[250:251], v[20:21], v[146:147]
	v_pk_fma_f32 v[244:245], v[24:25], v[252:253], v[244:245]
	v_pk_fma_f32 v[246:247], v[54:55], v[252:253], v[246:247]
	v_pk_fma_f32 v[248:249], v[16:17], v[252:253], v[248:249]
	v_pk_fma_f32 v[250:251], v[14:15], v[252:253], v[250:251]
	v_pk_fma_f32 v[244:245], v[28:29], v[158:159], v[244:245]
	v_pk_fma_f32 v[246:247], v[58:59], v[158:159], v[246:247]
	v_pk_fma_f32 v[248:249], v[18:19], v[158:159], v[248:249]
	v_pk_fma_f32 v[250:251], v[22:23], v[158:159], v[250:251]
	v_pk_fma_f32 v[244:245], v[30:31], v[148:149], v[244:245]
	v_pk_fma_f32 v[246:247], v[60:61], v[148:149], v[246:247]
	v_pk_fma_f32 v[248:249], v[2:3], v[148:149], v[248:249]
	v_pk_fma_f32 v[250:251], v[70:71], v[148:149], v[250:251]
	v_add_f32_e32 v160, 0, v244
	v_add_f32_e32 v194, 0, v246
	v_add_f32_e32 v231, 0, v248
	v_add_f32_e32 v232, 0, v250
	v_add_f32_e32 v160, v160, v245
	v_add_f32_e32 v194, v194, v247
	v_add_f32_e32 v231, v231, v249
	v_add_f32_e32 v232, v232, v251
	s_waitcnt vmcnt(12)
	v_mov_b32_e32 v252, v150
	v_mov_b32_e32 v253, v154
	v_mov_b32_e32 v154, v151
	v_mov_b32_e32 v158, v152
	v_mov_b32_e32 v159, v156
	v_mov_b32_e32 v156, v153
	v_pk_mul_f32 v[244:245], v[48:49], v[154:155]
	v_pk_mul_f32 v[246:247], v[64:65], v[154:155]
	v_pk_mul_f32 v[248:249], v[8:9], v[154:155]
	v_pk_mul_f32 v[250:251], v[74:75], v[154:155]
	v_pk_fma_f32 v[244:245], v[46:47], v[252:253], v[244:245]
	v_pk_fma_f32 v[246:247], v[62:63], v[252:253], v[246:247]
	v_pk_fma_f32 v[248:249], v[6:7], v[252:253], v[248:249]
	v_pk_fma_f32 v[250:251], v[72:73], v[252:253], v[250:251]
	v_pk_fma_f32 v[244:245], v[50:51], v[158:159], v[244:245]
	v_pk_fma_f32 v[246:247], v[66:67], v[158:159], v[246:247]
	v_pk_fma_f32 v[248:249], v[12:13], v[158:159], v[248:249]
	v_pk_fma_f32 v[250:251], v[76:77], v[158:159], v[250:251]
	v_pk_fma_f32 v[244:245], v[52:53], v[156:157], v[244:245]
	v_pk_fma_f32 v[246:247], v[68:69], v[156:157], v[246:247]
	v_pk_fma_f32 v[248:249], v[10:11], v[156:157], v[248:249]
	v_pk_fma_f32 v[250:251], v[78:79], v[156:157], v[250:251]
	v_add_f32_e32 v160, v160, v244
	v_add_f32_e32 v194, v194, v246
	v_add_f32_e32 v231, v231, v248
	v_add_f32_e32 v232, v232, v250
	v_add_f32_e32 v160, v160, v245
	v_add_f32_e32 v194, v194, v247
	v_add_f32_e32 v231, v231, v249
	v_add_f32_e32 v232, v232, v251
	v_cmp_eq_u32_e32 vcc, s0, v44
	v_add_f32_dpp v160, v160, v160 quad_perm:[1,0,3,2] row_mask:0xf bank_mask:0xf bound_ctrl:1
	v_add_f32_dpp v194, v194, v194 quad_perm:[1,0,3,2] row_mask:0xf bank_mask:0xf bound_ctrl:1
	v_add_f32_dpp v231, v231, v231 quad_perm:[1,0,3,2] row_mask:0xf bank_mask:0xf bound_ctrl:1
	v_add_f32_dpp v232, v232, v232 quad_perm:[1,0,3,2] row_mask:0xf bank_mask:0xf bound_ctrl:1
	v_add_f32_dpp v160, v160, v160 quad_perm:[2,3,0,1] row_mask:0xf bank_mask:0xf bound_ctrl:1
	v_add_f32_dpp v194, v194, v194 quad_perm:[2,3,0,1] row_mask:0xf bank_mask:0xf bound_ctrl:1
	v_add_f32_dpp v231, v231, v231 quad_perm:[2,3,0,1] row_mask:0xf bank_mask:0xf bound_ctrl:1
	v_add_f32_dpp v232, v232, v232 quad_perm:[2,3,0,1] row_mask:0xf bank_mask:0xf bound_ctrl:1
	v_add_f32_dpp v160, v160, v160 row_half_mirror row_mask:0xf bank_mask:0xf bound_ctrl:1
	v_add_f32_dpp v194, v194, v194 row_half_mirror row_mask:0xf bank_mask:0xf bound_ctrl:1
	v_add_f32_dpp v231, v231, v231 row_half_mirror row_mask:0xf bank_mask:0xf bound_ctrl:1
	v_add_f32_dpp v232, v232, v232 row_half_mirror row_mask:0xf bank_mask:0xf bound_ctrl:1
	v_add_f32_dpp v160, v160, v160 row_mirror row_mask:0xf bank_mask:0xf bound_ctrl:1
	v_add_f32_dpp v194, v194, v194 row_mirror row_mask:0xf bank_mask:0xf bound_ctrl:1
	v_add_f32_dpp v231, v231, v231 row_mirror row_mask:0xf bank_mask:0xf bound_ctrl:1
	v_add_f32_dpp v232, v232, v232 row_mirror row_mask:0xf bank_mask:0xf bound_ctrl:1
	v_readlane_b32 s3, v160, 16
	v_readlane_b32 s28, v160, 48
	v_readlane_b32 s29, v194, 16
	v_readlane_b32 s30, v194, 48
	v_readlane_b32 s24, v160, 0
	v_readlane_b32 s25, v194, 0
	v_readlane_b32 s26, v160, 32
	v_readlane_b32 s27, v194, 32
	v_mov_b32_e32 v94, s3
	v_mov_b32_e32 v95, s29
	v_mov_b32_e32 v96, s28
	v_mov_b32_e32 v97, s30
	v_pk_add_f32 v[94:95], s[24:25], v[94:95]
	v_pk_add_f32 v[96:97], s[26:27], v[96:97]
	v_readlane_b32 s3, v231, 16
	v_readlane_b32 s28, v231, 48
	v_readlane_b32 s29, v232, 16
	v_readlane_b32 s30, v232, 48
	v_readlane_b32 s24, v231, 0
	v_readlane_b32 s25, v232, 0
	v_readlane_b32 s26, v231, 32
	v_readlane_b32 s27, v232, 32
	v_pk_add_f32 v[94:95], v[94:95], v[96:97]
	v_mov_b32_e32 v98, s3
	v_mov_b32_e32 v99, s29
	v_mov_b32_e32 v100, s28
	v_mov_b32_e32 v101, s30
	v_cndmask_b32_e32 v82, v82, v94, vcc
	v_cndmask_b32_e32 v33, v33, v95, vcc
	v_pk_add_f32 v[98:99], s[24:25], v[98:99]
	v_pk_add_f32 v[100:101], s[26:27], v[100:101]
	s_waitcnt vmcnt(10)
; DEVI void phase_p7(const int TIDX, const int BIDX, const int GDIM, KAP KA, unsigned char* WSB, float* OUTB, int l, unsigned char* smem) {
;     ...
; #pragma unroll 4
;       for (int c = 0; c < 36; ++c) {
;         float4 wv[4];
; #pragma unroll
;         for (int j = 0; j < 4; ++j) wv[j] = *(const float4*)(WR + c * 1024 + j * 256 + lane * 4);
; #pragma unroll
;         for (int t = 0; t < 4; ++t) {
;           float s = 0.f;
; #pragma unroll
;           for (int j = 0; j < 4; ++j) s += v[t][j].x * wv[j].x + v[t][j].y * wv[j].y + v[t][j].z * wv[j].z + v[t][j].w * wv[j].w;
;           s = wave_sum(s);
;           if (lane == c) mine[t] = s;
;         }
;       }
	v_mov_b32_e32 v252, v162
	v_mov_b32_e32 v253, v166
	v_pk_add_f32 v[98:99], v[98:99], v[100:101]
	v_mov_b32_e32 v166, v163
	v_mov_b32_e32 v158, v164
	v_mov_b32_e32 v159, v168
	v_mov_b32_e32 v168, v165
	v_cndmask_b32_e32 v0, v0, v98, vcc
	v_cndmask_b32_e32 v1, v1, v99, vcc
	v_pk_mul_f32 v[244:245], v[26:27], v[166:167]
	v_pk_mul_f32 v[246:247], v[56:57], v[166:167]
	v_pk_mul_f32 v[248:249], v[4:5], v[166:167]
	v_pk_mul_f32 v[250:251], v[20:21], v[166:167]
	v_pk_fma_f32 v[244:245], v[24:25], v[252:253], v[244:245]
	v_pk_fma_f32 v[246:247], v[54:55], v[252:253], v[246:247]
	v_pk_fma_f32 v[248:249], v[16:17], v[252:253], v[248:249]
	v_pk_fma_f32 v[250:251], v[14:15], v[252:253], v[250:251]
	v_pk_fma_f32 v[244:245], v[28:29], v[158:159], v[244:245]
	v_pk_fma_f32 v[246:247], v[58:59], v[158:159], v[246:247]
	v_pk_fma_f32 v[248:249], v[18:19], v[158:159], v[248:249]
	v_pk_fma_f32 v[250:251], v[22:23], v[158:159], v[250:251]
	v_pk_fma_f32 v[244:245], v[30:31], v[168:169], v[244:245]
	v_pk_fma_f32 v[246:247], v[60:61], v[168:169], v[246:247]
	v_pk_fma_f32 v[248:249], v[2:3], v[168:169], v[248:249]
	v_pk_fma_f32 v[250:251], v[70:71], v[168:169], v[250:251]
	v_add_f32_e32 v160, 0, v244
	v_add_f32_e32 v194, 0, v246
	v_add_f32_e32 v231, 0, v248
	v_add_f32_e32 v232, 0, v250
	v_add_f32_e32 v160, v160, v245
	v_add_f32_e32 v194, v194, v247
	v_add_f32_e32 v231, v231, v249
	v_add_f32_e32 v232, v232, v251
	s_waitcnt vmcnt(8)
	v_mov_b32_e32 v252, v170
	v_mov_b32_e32 v253, v174
	v_mov_b32_e32 v174, v171
	v_mov_b32_e32 v158, v172
	v_mov_b32_e32 v159, v176
	v_mov_b32_e32 v176, v173
	v_pk_mul_f32 v[244:245], v[48:49], v[174:175]
	v_pk_mul_f32 v[246:247], v[64:65], v[174:175]
	v_pk_mul_f32 v[248:249], v[8:9], v[174:175]
	v_pk_mul_f32 v[250:251], v[74:75], v[174:175]
	v_pk_fma_f32 v[244:245], v[46:47], v[252:253], v[244:245]
	v_pk_fma_f32 v[246:247], v[62:63], v[252:253], v[246:247]
	v_pk_fma_f32 v[248:249], v[6:7], v[252:253], v[248:249]
	v_pk_fma_f32 v[250:251], v[72:73], v[252:253], v[250:251]
	v_pk_fma_f32 v[244:245], v[50:51], v[158:159], v[244:245]
	v_pk_fma_f32 v[246:247], v[66:67], v[158:159], v[246:247]
	v_pk_fma_f32 v[248:249], v[12:13], v[158:159], v[248:249]
	v_pk_fma_f32 v[250:251], v[76:77], v[158:159], v[250:251]
	v_pk_fma_f32 v[244:245], v[52:53], v[176:177], v[244:245]
	v_pk_fma_f32 v[246:247], v[68:69], v[176:177], v[246:247]
	v_pk_fma_f32 v[248:249], v[10:11], v[176:177], v[248:249]
	v_pk_fma_f32 v[250:251], v[78:79], v[176:177], v[250:251]
	v_add_f32_e32 v160, v160, v244
	v_add_f32_e32 v194, v194, v246
	v_add_f32_e32 v231, v231, v248
	v_add_f32_e32 v232, v232, v250
	v_add_f32_e32 v160, v160, v245
	v_add_f32_e32 v194, v194, v247
	v_add_f32_e32 v231, v231, v249
	v_add_f32_e32 v232, v232, v251
	s_or_b32 s101, s2, 1
	v_cmp_eq_u32_e32 vcc, s101, v45
	v_add_f32_dpp v160, v160, v160 quad_perm:[1,0,3,2] row_mask:0xf bank_mask:0xf bound_ctrl:1
	v_add_f32_dpp v194, v194, v194 quad_perm:[1,0,3,2] row_mask:0xf bank_mask:0xf bound_ctrl:1
	v_add_f32_dpp v231, v231, v231 quad_perm:[1,0,3,2] row_mask:0xf bank_mask:0xf bound_ctrl:1
	v_add_f32_dpp v232, v232, v232 quad_perm:[1,0,3,2] row_mask:0xf bank_mask:0xf bound_ctrl:1
	v_add_f32_dpp v160, v160, v160 quad_perm:[2,3,0,1] row_mask:0xf bank_mask:0xf bound_ctrl:1
	v_add_f32_dpp v194, v194, v194 quad_perm:[2,3,0,1] row_mask:0xf bank_mask:0xf bound_ctrl:1
	v_add_f32_dpp v231, v231, v231 quad_perm:[2,3,0,1] row_mask:0xf bank_mask:0xf bound_ctrl:1
	v_add_f32_dpp v232, v232, v232 quad_perm:[2,3,0,1] row_mask:0xf bank_mask:0xf bound_ctrl:1
	v_add_f32_dpp v160, v160, v160 row_half_mirror row_mask:0xf bank_mask:0xf bound_ctrl:1
	v_add_f32_dpp v194, v194, v194 row_half_mirror row_mask:0xf bank_mask:0xf bound_ctrl:1
	v_add_f32_dpp v231, v231, v231 row_half_mirror row_mask:0xf bank_mask:0xf bound_ctrl:1
	v_add_f32_dpp v232, v232, v232 row_half_mirror row_mask:0xf bank_mask:0xf bound_ctrl:1
	v_add_f32_dpp v160, v160, v160 row_mirror row_mask:0xf bank_mask:0xf bound_ctrl:1
	v_add_f32_dpp v194, v194, v194 row_mirror row_mask:0xf bank_mask:0xf bound_ctrl:1
	v_add_f32_dpp v231, v231, v231 row_mirror row_mask:0xf bank_mask:0xf bound_ctrl:1
	v_add_f32_dpp v232, v232, v232 row_mirror row_mask:0xf bank_mask:0xf bound_ctrl:1
	v_readlane_b32 s3, v160, 16
	v_readlane_b32 s28, v160, 48
	v_readlane_b32 s29, v194, 16
	v_readlane_b32 s30, v194, 48
	v_readlane_b32 s24, v160, 0
	v_readlane_b32 s25, v194, 0
	v_readlane_b32 s26, v160, 32
	v_readlane_b32 s27, v194, 32
	v_mov_b32_e32 v94, s3
	v_mov_b32_e32 v95, s29
	v_mov_b32_e32 v96, s28
	v_mov_b32_e32 v97, s30
	v_pk_add_f32 v[94:95], s[24:25], v[94:95]
	v_pk_add_f32 v[96:97], s[26:27], v[96:97]
	v_readlane_b32 s3, v231, 16
	v_readlane_b32 s28, v231, 48
	v_readlane_b32 s29, v232, 16
	v_readlane_b32 s30, v232, 48
	v_readlane_b32 s24, v231, 0
	v_readlane_b32 s25, v232, 0
	v_readlane_b32 s26, v231, 32
	v_readlane_b32 s27, v232, 32
	v_pk_add_f32 v[94:95], v[94:95], v[96:97]
	v_mov_b32_e32 v98, s3
	v_mov_b32_e32 v99, s29
	v_mov_b32_e32 v100, s28
	v_mov_b32_e32 v101, s30
	v_cndmask_b32_e32 v82, v82, v94, vcc
	v_cndmask_b32_e32 v33, v33, v95, vcc
	v_pk_add_f32 v[98:99], s[24:25], v[98:99]
	v_pk_add_f32 v[100:101], s[26:27], v[100:101]
	s_waitcnt vmcnt(6)
; DEVI void phase_p7(const int TIDX, const int BIDX, const int GDIM, KAP KA, unsigned char* WSB, float* OUTB, int l, unsigned char* smem) {
;     ...
; #pragma unroll 4
;       for (int c = 0; c < 36; ++c) {
;         float4 wv[4];
; #pragma unroll
;         for (int j = 0; j < 4; ++j) wv[j] = *(const float4*)(WR + c * 1024 + j * 256 + lane * 4);
; #pragma unroll
;         for (int t = 0; t < 4; ++t) {
;           float s = 0.f;
; #pragma unroll
;           for (int j = 0; j < 4; ++j) s += v[t][j].x * wv[j].x + v[t][j].y * wv[j].y + v[t][j].z * wv[j].z + v[t][j].w * wv[j].w;
;           s = wave_sum(s);
;           if (lane == c) mine[t] = s;
;         }
;       }
	v_mov_b32_e32 v252, v178
	v_mov_b32_e32 v253, v182
	v_pk_add_f32 v[98:99], v[98:99], v[100:101]
	v_mov_b32_e32 v182, v179
	v_mov_b32_e32 v158, v180
	v_mov_b32_e32 v159, v184
	v_mov_b32_e32 v184, v181
	v_cndmask_b32_e32 v0, v0, v98, vcc
	v_cndmask_b32_e32 v1, v1, v99, vcc
	v_pk_mul_f32 v[244:245], v[26:27], v[182:183]
	v_pk_mul_f32 v[246:247], v[56:57], v[182:183]
	v_pk_mul_f32 v[248:249], v[4:5], v[182:183]
	v_pk_mul_f32 v[250:251], v[20:21], v[182:183]
	v_pk_fma_f32 v[244:245], v[24:25], v[252:253], v[244:245]
	v_pk_fma_f32 v[246:247], v[54:55], v[252:253], v[246:247]
	v_pk_fma_f32 v[248:249], v[16:17], v[252:253], v[248:249]
	v_pk_fma_f32 v[250:251], v[14:15], v[252:253], v[250:251]
	v_pk_fma_f32 v[244:245], v[28:29], v[158:159], v[244:245]
	v_pk_fma_f32 v[246:247], v[58:59], v[158:159], v[246:247]
	v_pk_fma_f32 v[248:249], v[18:19], v[158:159], v[248:249]
	v_pk_fma_f32 v[250:251], v[22:23], v[158:159], v[250:251]
	v_pk_fma_f32 v[244:245], v[30:31], v[184:185], v[244:245]
	v_pk_fma_f32 v[246:247], v[60:61], v[184:185], v[246:247]
	v_pk_fma_f32 v[248:249], v[2:3], v[184:185], v[248:249]
	v_pk_fma_f32 v[250:251], v[70:71], v[184:185], v[250:251]
	v_add_f32_e32 v160, 0, v244
	v_add_f32_e32 v194, 0, v246
	v_add_f32_e32 v231, 0, v248
	v_add_f32_e32 v232, 0, v250
	v_add_f32_e32 v160, v160, v245
	v_add_f32_e32 v194, v194, v247
	v_add_f32_e32 v231, v231, v249
	v_add_f32_e32 v232, v232, v251
	s_waitcnt vmcnt(4)
	v_mov_b32_e32 v252, v186
	v_mov_b32_e32 v253, v190
	v_mov_b32_e32 v190, v187
	v_mov_b32_e32 v158, v188
	v_mov_b32_e32 v159, v192
	v_mov_b32_e32 v192, v189
	v_pk_mul_f32 v[244:245], v[48:49], v[190:191]
	v_pk_mul_f32 v[246:247], v[64:65], v[190:191]
	v_pk_mul_f32 v[248:249], v[8:9], v[190:191]
	v_pk_mul_f32 v[250:251], v[74:75], v[190:191]
	v_pk_fma_f32 v[244:245], v[46:47], v[252:253], v[244:245]
	v_pk_fma_f32 v[246:247], v[62:63], v[252:253], v[246:247]
	v_pk_fma_f32 v[248:249], v[6:7], v[252:253], v[248:249]
	v_pk_fma_f32 v[250:251], v[72:73], v[252:253], v[250:251]
	v_pk_fma_f32 v[244:245], v[50:51], v[158:159], v[244:245]
	v_pk_fma_f32 v[246:247], v[66:67], v[158:159], v[246:247]
	v_pk_fma_f32 v[248:249], v[12:13], v[158:159], v[248:249]
	v_pk_fma_f32 v[250:251], v[76:77], v[158:159], v[250:251]
	v_pk_fma_f32 v[244:245], v[52:53], v[192:193], v[244:245]
	v_pk_fma_f32 v[246:247], v[68:69], v[192:193], v[246:247]
	v_pk_fma_f32 v[248:249], v[10:11], v[192:193], v[248:249]
	v_pk_fma_f32 v[250:251], v[78:79], v[192:193], v[250:251]
	v_add_f32_e32 v160, v160, v244
	v_add_f32_e32 v194, v194, v246
	v_add_f32_e32 v231, v231, v248
	v_add_f32_e32 v232, v232, v250
	v_add_f32_e32 v160, v160, v245
	v_add_f32_e32 v194, v194, v247
	v_add_f32_e32 v231, v231, v249
	v_add_f32_e32 v232, v232, v251
	s_or_b32 s101, s2, 2
	v_cmp_eq_u32_e32 vcc, s101, v45
	v_add_f32_dpp v160, v160, v160 quad_perm:[1,0,3,2] row_mask:0xf bank_mask:0xf bound_ctrl:1
	v_add_f32_dpp v194, v194, v194 quad_perm:[1,0,3,2] row_mask:0xf bank_mask:0xf bound_ctrl:1
	v_add_f32_dpp v231, v231, v231 quad_perm:[1,0,3,2] row_mask:0xf bank_mask:0xf bound_ctrl:1
	v_add_f32_dpp v232, v232, v232 quad_perm:[1,0,3,2] row_mask:0xf bank_mask:0xf bound_ctrl:1
	v_add_f32_dpp v160, v160, v160 quad_perm:[2,3,0,1] row_mask:0xf bank_mask:0xf bound_ctrl:1
	v_add_f32_dpp v194, v194, v194 quad_perm:[2,3,0,1] row_mask:0xf bank_mask:0xf bound_ctrl:1
	v_add_f32_dpp v231, v231, v231 quad_perm:[2,3,0,1] row_mask:0xf bank_mask:0xf bound_ctrl:1
	v_add_f32_dpp v232, v232, v232 quad_perm:[2,3,0,1] row_mask:0xf bank_mask:0xf bound_ctrl:1
	v_add_f32_dpp v160, v160, v160 row_half_mirror row_mask:0xf bank_mask:0xf bound_ctrl:1
	v_add_f32_dpp v194, v194, v194 row_half_mirror row_mask:0xf bank_mask:0xf bound_ctrl:1
	v_add_f32_dpp v231, v231, v231 row_half_mirror row_mask:0xf bank_mask:0xf bound_ctrl:1
	v_add_f32_dpp v232, v232, v232 row_half_mirror row_mask:0xf bank_mask:0xf bound_ctrl:1
	v_add_f32_dpp v160, v160, v160 row_mirror row_mask:0xf bank_mask:0xf bound_ctrl:1
	v_add_f32_dpp v194, v194, v194 row_mirror row_mask:0xf bank_mask:0xf bound_ctrl:1
	v_add_f32_dpp v231, v231, v231 row_mirror row_mask:0xf bank_mask:0xf bound_ctrl:1
	v_add_f32_dpp v232, v232, v232 row_mirror row_mask:0xf bank_mask:0xf bound_ctrl:1
	v_readlane_b32 s3, v160, 16
	v_readlane_b32 s28, v160, 48
	v_readlane_b32 s29, v194, 16
	v_readlane_b32 s30, v194, 48
	v_readlane_b32 s24, v160, 0
	v_readlane_b32 s25, v194, 0
	v_readlane_b32 s26, v160, 32
	v_readlane_b32 s27, v194, 32
	v_mov_b32_e32 v94, s3
	v_mov_b32_e32 v95, s29
	v_mov_b32_e32 v96, s28
	v_mov_b32_e32 v97, s30
	v_pk_add_f32 v[94:95], s[24:25], v[94:95]
	v_pk_add_f32 v[96:97], s[26:27], v[96:97]
	v_readlane_b32 s3, v231, 16
	v_readlane_b32 s28, v231, 48
	v_readlane_b32 s29, v232, 16
	v_readlane_b32 s30, v232, 48
	v_readlane_b32 s24, v231, 0
	v_readlane_b32 s25, v232, 0
	v_readlane_b32 s26, v231, 32
	v_readlane_b32 s27, v232, 32
	v_pk_add_f32 v[94:95], v[94:95], v[96:97]
	v_mov_b32_e32 v98, s3
	v_mov_b32_e32 v99, s29
	v_mov_b32_e32 v100, s28
	v_mov_b32_e32 v101, s30
	v_cndmask_b32_e32 v82, v82, v94, vcc
	v_cndmask_b32_e32 v33, v33, v95, vcc
	v_pk_add_f32 v[98:99], s[24:25], v[98:99]
	v_pk_add_f32 v[100:101], s[26:27], v[100:101]
	s_waitcnt vmcnt(2)
; DEVI void phase_p7(const int TIDX, const int BIDX, const int GDIM, KAP KA, unsigned char* WSB, float* OUTB, int l, unsigned char* smem) {
;     ...
; #pragma unroll 4
;       for (int c = 0; c < 36; ++c) {
;         float4 wv[4];
; #pragma unroll
;         for (int j = 0; j < 4; ++j) wv[j] = *(const float4*)(WR + c * 1024 + j * 256 + lane * 4);
; #pragma unroll
;         for (int t = 0; t < 4; ++t) {
;           float s = 0.f;
; #pragma unroll
;           for (int j = 0; j < 4; ++j) s += v[t][j].x * wv[j].x + v[t][j].y * wv[j].y + v[t][j].z * wv[j].z + v[t][j].w * wv[j].w;
;           s = wave_sum(s);
;           if (lane == c) mine[t] = s;
;         }
;       }
	v_mov_b32_e32 v252, v196
	v_mov_b32_e32 v253, v200
	v_pk_add_f32 v[98:99], v[98:99], v[100:101]
	v_mov_b32_e32 v200, v197
	v_mov_b32_e32 v158, v198
	v_mov_b32_e32 v159, v202
	v_mov_b32_e32 v202, v199
	v_cndmask_b32_e32 v0, v0, v98, vcc
	v_cndmask_b32_e32 v1, v1, v99, vcc
	v_pk_mul_f32 v[244:245], v[26:27], v[200:201]
	v_pk_mul_f32 v[246:247], v[56:57], v[200:201]
	v_pk_mul_f32 v[248:249], v[4:5], v[200:201]
	v_pk_mul_f32 v[250:251], v[20:21], v[200:201]
	v_pk_fma_f32 v[244:245], v[24:25], v[252:253], v[244:245]
	v_pk_fma_f32 v[246:247], v[54:55], v[252:253], v[246:247]
	v_pk_fma_f32 v[248:249], v[16:17], v[252:253], v[248:249]
	v_pk_fma_f32 v[250:251], v[14:15], v[252:253], v[250:251]
	v_pk_fma_f32 v[244:245], v[28:29], v[158:159], v[244:245]
	v_pk_fma_f32 v[246:247], v[58:59], v[158:159], v[246:247]
	v_pk_fma_f32 v[248:249], v[18:19], v[158:159], v[248:249]
	v_pk_fma_f32 v[250:251], v[22:23], v[158:159], v[250:251]
	v_pk_fma_f32 v[244:245], v[30:31], v[202:203], v[244:245]
	v_pk_fma_f32 v[246:247], v[60:61], v[202:203], v[246:247]
	v_pk_fma_f32 v[248:249], v[2:3], v[202:203], v[248:249]
	v_pk_fma_f32 v[250:251], v[70:71], v[202:203], v[250:251]
	v_add_f32_e32 v160, 0, v244
	v_add_f32_e32 v194, 0, v246
	v_add_f32_e32 v231, 0, v248
	v_add_f32_e32 v232, 0, v250
	v_add_f32_e32 v160, v160, v245
	v_add_f32_e32 v194, v194, v247
	v_add_f32_e32 v231, v231, v249
	v_add_f32_e32 v232, v232, v251
	s_waitcnt vmcnt(0)
	v_mov_b32_e32 v252, v236
	v_mov_b32_e32 v253, v240
	v_mov_b32_e32 v240, v237
	v_mov_b32_e32 v158, v238
	v_mov_b32_e32 v159, v242
	v_mov_b32_e32 v242, v239
	v_pk_mul_f32 v[244:245], v[48:49], v[240:241]
	v_pk_mul_f32 v[246:247], v[64:65], v[240:241]
	v_pk_mul_f32 v[248:249], v[8:9], v[240:241]
	v_pk_mul_f32 v[250:251], v[74:75], v[240:241]
	v_pk_fma_f32 v[244:245], v[46:47], v[252:253], v[244:245]
	v_pk_fma_f32 v[246:247], v[62:63], v[252:253], v[246:247]
	v_pk_fma_f32 v[248:249], v[6:7], v[252:253], v[248:249]
	v_pk_fma_f32 v[250:251], v[72:73], v[252:253], v[250:251]
	v_pk_fma_f32 v[244:245], v[50:51], v[158:159], v[244:245]
	v_pk_fma_f32 v[246:247], v[66:67], v[158:159], v[246:247]
	v_pk_fma_f32 v[248:249], v[12:13], v[158:159], v[248:249]
	v_pk_fma_f32 v[250:251], v[76:77], v[158:159], v[250:251]
	v_pk_fma_f32 v[244:245], v[52:53], v[242:243], v[244:245]
	v_pk_fma_f32 v[246:247], v[68:69], v[242:243], v[246:247]
	v_pk_fma_f32 v[248:249], v[10:11], v[242:243], v[248:249]
	v_pk_fma_f32 v[250:251], v[78:79], v[242:243], v[250:251]
	v_add_f32_e32 v160, v160, v244
	v_add_f32_e32 v194, v194, v246
	v_add_f32_e32 v231, v231, v248
	v_add_f32_e32 v232, v232, v250
	v_add_f32_e32 v160, v160, v245
	v_add_f32_e32 v194, v194, v247
	v_add_f32_e32 v231, v231, v249
	v_add_f32_e32 v232, v232, v251
	s_or_b32 s101, s2, 3
	v_cmp_eq_u32_e32 vcc, s101, v45
	v_add_f32_dpp v160, v160, v160 quad_perm:[1,0,3,2] row_mask:0xf bank_mask:0xf bound_ctrl:1
	v_add_f32_dpp v194, v194, v194 quad_perm:[1,0,3,2] row_mask:0xf bank_mask:0xf bound_ctrl:1
	v_add_f32_dpp v231, v231, v231 quad_perm:[1,0,3,2] row_mask:0xf bank_mask:0xf bound_ctrl:1
	v_add_f32_dpp v232, v232, v232 quad_perm:[1,0,3,2] row_mask:0xf bank_mask:0xf bound_ctrl:1
	v_add_f32_dpp v160, v160, v160 quad_perm:[2,3,0,1] row_mask:0xf bank_mask:0xf bound_ctrl:1
	v_add_f32_dpp v194, v194, v194 quad_perm:[2,3,0,1] row_mask:0xf bank_mask:0xf bound_ctrl:1
	v_add_f32_dpp v231, v231, v231 quad_perm:[2,3,0,1] row_mask:0xf bank_mask:0xf bound_ctrl:1
	v_add_f32_dpp v232, v232, v232 quad_perm:[2,3,0,1] row_mask:0xf bank_mask:0xf bound_ctrl:1
	v_add_f32_dpp v160, v160, v160 row_half_mirror row_mask:0xf bank_mask:0xf bound_ctrl:1
	v_add_f32_dpp v194, v194, v194 row_half_mirror row_mask:0xf bank_mask:0xf bound_ctrl:1
	v_add_f32_dpp v231, v231, v231 row_half_mirror row_mask:0xf bank_mask:0xf bound_ctrl:1
	v_add_f32_dpp v232, v232, v232 row_half_mirror row_mask:0xf bank_mask:0xf bound_ctrl:1
	v_add_f32_dpp v160, v160, v160 row_mirror row_mask:0xf bank_mask:0xf bound_ctrl:1
	v_add_f32_dpp v194, v194, v194 row_mirror row_mask:0xf bank_mask:0xf bound_ctrl:1
	v_add_f32_dpp v231, v231, v231 row_mirror row_mask:0xf bank_mask:0xf bound_ctrl:1
	v_add_f32_dpp v232, v232, v232 row_mirror row_mask:0xf bank_mask:0xf bound_ctrl:1
	v_readlane_b32 s3, v160, 16
	v_readlane_b32 s28, v160, 48
	v_readlane_b32 s29, v194, 16
	v_readlane_b32 s30, v194, 48
	v_readlane_b32 s24, v160, 0
	v_readlane_b32 s25, v194, 0
	v_readlane_b32 s26, v160, 32
	v_readlane_b32 s27, v194, 32
	v_mov_b32_e32 v94, s3
	v_mov_b32_e32 v95, s29
	v_mov_b32_e32 v96, s28
	v_mov_b32_e32 v97, s30
	v_pk_add_f32 v[94:95], s[24:25], v[94:95]
	v_pk_add_f32 v[96:97], s[26:27], v[96:97]
	v_readlane_b32 s3, v231, 16
	v_readlane_b32 s28, v231, 48
	v_readlane_b32 s29, v232, 16
	v_readlane_b32 s30, v232, 48
	v_readlane_b32 s24, v231, 0
	v_readlane_b32 s25, v232, 0
	v_readlane_b32 s26, v231, 32
	v_readlane_b32 s27, v232, 32
	v_pk_add_f32 v[94:95], v[94:95], v[96:97]
	v_mov_b32_e32 v98, s3
	v_mov_b32_e32 v99, s29
	v_mov_b32_e32 v100, s28
	v_mov_b32_e32 v101, s30
	v_cndmask_b32_e32 v82, v82, v94, vcc
	v_cndmask_b32_e32 v33, v33, v95, vcc
	v_pk_add_f32 v[98:99], s[24:25], v[98:99]
	v_pk_add_f32 v[100:101], s[26:27], v[100:101]
	s_add_i32 s2, s2, 4
	v_pk_add_f32 v[98:99], v[98:99], v[100:101]
	s_add_u32 s0, s0, 0x4000
	s_addc_u32 s1, s1, 0
	v_cndmask_b32_e32 v0, v0, v98, vcc
	v_cndmask_b32_e32 v1, v1, v99, vcc
	s_cmp_eq_u32 s2, 36
	s_cbranch_scc0 .LBB0_69
; DEVI void phase_p7(const int TIDX, const int BIDX, const int GDIM, KAP KA, unsigned char* WSB, float* OUTB, int l, unsigned char* smem) {
;     ...
;         float gl[4];
; #pragma unroll
;         for (int j = 0; j < 4; ++j) gl[j] = __shfl(mine[t], j);
;         int gi = 0; float gm = gl[0];
; #pragma unroll
;         for (int j = 1; j < 4; ++j) if (gl[j] > gm) { gm = gl[j]; gi = j; }
;         float gs = 0.f;
; #pragma unroll
;         for (int j = 0; j < 4; ++j) gs += expf(gl[j] - gm);
;         const float gtop = 1.f / gs;
;         float el[8];
; #pragma unroll
;         for (int j = 0; j < 8; ++j) el[j] = __shfl(mine[t], 4 + gi * 8 + j);
;         float em = el[0];
; #pragma unroll
;         for (int j = 1; j < 8; ++j) em = fmaxf(em, el[j]);
;         float pe[8], es = 0.f;
; #pragma unroll
;         for (int j = 0; j < 8; ++j) { pe[j] = expf(el[j] - em); es += pe[j]; }
	ds_bpermute_b32 v2, v85, v82
	ds_bpermute_b32 v3, v86, v82
	ds_bpermute_b32 v4, v87, v82
	ds_bpermute_b32 v5, v88, v82
	s_waitcnt lgkmcnt(2)
	v_cmp_gt_f32_e32 vcc, v3, v2
	s_nop 1
	v_cndmask_b32_e32 v6, v2, v3, vcc
	s_waitcnt lgkmcnt(1)
	v_cmp_lt_f32_e64 s[22:23], v6, v4
	s_nop 1
	v_cndmask_b32_e64 v6, v6, v4, s[22:23]
	s_waitcnt lgkmcnt(0)
	v_cmp_lt_f32_e64 s[24:25], v6, v5
	s_nop 1
	v_cndmask_b32_e64 v6, v6, v5, s[24:25]
	v_sub_f32_e32 v7, v2, v6
	v_sub_f32_e32 v2, v3, v6
	v_mul_f32_e32 v3, 0x3fb8aa3b, v2
	v_fma_f32 v8, v2, s61, -v3
	v_rndne_f32_e32 v9, v3
	v_fmac_f32_e32 v8, 0x32a5705f, v2
	v_sub_f32_e32 v3, v3, v9
	v_add_f32_e32 v3, v3, v8
	v_exp_f32_e32 v3, v3
	v_cvt_i32_f32_e32 v8, v9
	v_cmp_ngt_f32_e64 s[26:27], s90, v2
	v_mul_f32_e32 v16, 0x3fb8aa3b, v7
	v_fma_f32 v17, v7, s61, -v16
	v_ldexp_f32 v3, v3, v8
	v_cndmask_b32_e64 v3, 0, v3, s[26:27]
	v_cmp_nlt_f32_e64 s[26:27], s91, v2
	v_sub_f32_e32 v2, v4, v6
	v_mul_f32_e32 v4, 0x3fb8aa3b, v2
	v_fma_f32 v8, v2, s61, -v4
	v_rndne_f32_e32 v9, v4
	v_fmac_f32_e32 v8, 0x32a5705f, v2
	v_sub_f32_e32 v4, v4, v9
	v_add_f32_e32 v4, v4, v8
	v_exp_f32_e32 v4, v4
	v_cvt_i32_f32_e32 v8, v9
	v_cndmask_b32_e64 v3, v229, v3, s[26:27]
	v_cmp_ngt_f32_e64 s[26:27], s90, v2
	v_rndne_f32_e32 v18, v16
	v_ldexp_f32 v4, v4, v8
	v_cndmask_b32_e64 v4, 0, v4, s[26:27]
	v_cmp_nlt_f32_e64 s[26:27], s91, v2
	v_sub_f32_e32 v2, v5, v6
	v_mul_f32_e32 v5, 0x3fb8aa3b, v2
	v_fma_f32 v6, v2, s61, -v5
	v_rndne_f32_e32 v8, v5
	v_fmac_f32_e32 v6, 0x32a5705f, v2
	v_sub_f32_e32 v5, v5, v8
	v_add_f32_e32 v5, v5, v6
	v_exp_f32_e32 v5, v5
	v_cvt_i32_f32_e32 v6, v8
	v_cndmask_b32_e64 v4, v229, v4, s[26:27]
	v_cmp_ngt_f32_e64 s[26:27], s90, v2
	v_fmac_f32_e32 v17, 0x32a5705f, v7
	v_ldexp_f32 v5, v5, v6
	v_cndmask_b32_e64 v5, 0, v5, s[26:27]
	v_cmp_nlt_f32_e64 s[26:27], s91, v2
	v_sub_f32_e32 v16, v16, v18
	v_add_f32_e32 v16, v16, v17
	v_cndmask_b32_e64 v6, v229, v5, s[26:27]
	v_cndmask_b32_e64 v5, 0, 8, vcc
	v_cndmask_b32_e64 v5, v5, 16, s[22:23]
	v_exp_f32_e32 v16, v16
	v_cvt_i32_f32_e32 v17, v18
	v_cndmask_b32_e64 v5, v5, 24, s[24:25]
	v_or_b32_e32 v8, v5, v84
	v_lshlrev_b32_e32 v8, 2, v8
	ds_bpermute_b32 v9, v8, v82
	ds_bpermute_b32 v10, v8, v82 offset:4
	v_ldexp_f32 v16, v16, v17
	v_cmp_ngt_f32_e32 vcc, s90, v7
	ds_bpermute_b32 v11, v8, v82 offset:8
	ds_bpermute_b32 v12, v8, v82 offset:12
	v_cndmask_b32_e32 v16, 0, v16, vcc
	v_cmp_nlt_f32_e32 vcc, s91, v7
	ds_bpermute_b32 v13, v8, v82 offset:16
	ds_bpermute_b32 v14, v8, v82 offset:20
	v_cndmask_b32_e32 v7, v229, v16, vcc
	v_add_f32_e32 v3, v7, v3
	ds_bpermute_b32 v15, v8, v82 offset:24
	ds_bpermute_b32 v8, v8, v82 offset:28
	v_add_f32_e32 v3, v4, v3
	v_add_f32_e32 v3, v6, v3
	s_waitcnt lgkmcnt(6)
	v_max_f32_e32 v4, v10, v10
	v_max_f32_e32 v6, v9, v9
	v_max_f32_e32 v4, v6, v4
	s_waitcnt lgkmcnt(4)
	v_max3_f32 v4, v4, v11, v12
	s_waitcnt lgkmcnt(2)
	v_max3_f32 v4, v4, v13, v14
	s_waitcnt lgkmcnt(0)
	v_max3_f32 v4, v4, v15, v8
	v_sub_f32_e32 v6, v9, v4
	v_mul_f32_e32 v7, 0x3fb8aa3b, v6
	v_fma_f32 v9, v6, s61, -v7
	v_rndne_f32_e32 v16, v7
	v_fmac_f32_e32 v9, 0x32a5705f, v6
	v_sub_f32_e32 v7, v7, v16
	v_add_f32_e32 v7, v7, v9
	v_exp_f32_e32 v7, v7
	v_cvt_i32_f32_e32 v9, v16
	v_cmp_ngt_f32_e32 vcc, s90, v6
	v_mov_b32_e32 v2, 0
	v_ldexp_f32 v7, v7, v9
	v_cndmask_b32_e32 v7, 0, v7, vcc
	v_cmp_nlt_f32_e32 vcc, s91, v6
	s_nop 1
	v_cndmask_b32_e32 v6, v229, v7, vcc
	v_sub_f32_e32 v7, v10, v4
	v_mul_f32_e32 v9, 0x3fb8aa3b, v7
	v_fma_f32 v10, v7, s61, -v9
	v_rndne_f32_e32 v16, v9
	v_fmac_f32_e32 v10, 0x32a5705f, v7
	v_sub_f32_e32 v9, v9, v16
	v_add_f32_e32 v9, v9, v10
	v_exp_f32_e32 v9, v9
	v_cvt_i32_f32_e32 v10, v16
	v_cmp_ngt_f32_e32 vcc, s90, v7
	v_ldexp_f32 v9, v9, v10
	v_sub_f32_e32 v10, v11, v4
	v_mul_f32_e32 v11, 0x3fb8aa3b, v10
	v_fma_f32 v16, v10, s61, -v11
	v_rndne_f32_e32 v17, v11
	v_fmac_f32_e32 v16, 0x32a5705f, v10
	v_sub_f32_e32 v11, v11, v17
	v_add_f32_e32 v11, v11, v16
	v_exp_f32_e32 v11, v11
	v_cvt_i32_f32_e32 v16, v17
	v_cndmask_b32_e32 v9, 0, v9, vcc
	v_cmp_nlt_f32_e32 vcc, s91, v7
	v_ldexp_f32 v11, v11, v16
	s_nop 0
	v_cndmask_b32_e32 v7, v229, v9, vcc
	v_cmp_ngt_f32_e32 vcc, s90, v10
	v_add_f32_e32 v9, v6, v7
	s_nop 0
	v_cndmask_b32_e32 v11, 0, v11, vcc
	v_cmp_nlt_f32_e32 vcc, s91, v10
	s_nop 1
	v_cndmask_b32_e32 v10, v229, v11, vcc
	v_sub_f32_e32 v11, v12, v4
	v_mul_f32_e32 v12, 0x3fb8aa3b, v11
	v_fma_f32 v16, v11, s61, -v12
	v_rndne_f32_e32 v17, v12
	v_fmac_f32_e32 v16, 0x32a5705f, v11
	v_sub_f32_e32 v12, v12, v17
	v_add_f32_e32 v12, v12, v16
	v_exp_f32_e32 v12, v12
	v_cvt_i32_f32_e32 v16, v17
	v_cmp_ngt_f32_e32 vcc, s90, v11
	v_add_f32_e32 v9, v10, v9
	v_ldexp_f32 v12, v12, v16
	v_cndmask_b32_e32 v12, 0, v12, vcc
	v_cmp_nlt_f32_e32 vcc, s91, v11
	s_nop 1
	v_cndmask_b32_e32 v11, v229, v12, vcc
	v_sub_f32_e32 v12, v13, v4
	v_mul_f32_e32 v13, 0x3fb8aa3b, v12
	v_fma_f32 v16, v12, s61, -v13
	v_rndne_f32_e32 v17, v13
	v_fmac_f32_e32 v16, 0x32a5705f, v12
	v_sub_f32_e32 v13, v13, v17
	v_add_f32_e32 v13, v13, v16
	v_exp_f32_e32 v13, v13
	v_cvt_i32_f32_e32 v16, v17
	v_cmp_ngt_f32_e32 vcc, s90, v12
	v_add_f32_e32 v9, v11, v9
	v_ldexp_f32 v13, v13, v16
	v_cndmask_b32_e32 v13, 0, v13, vcc
	v_cmp_nlt_f32_e32 vcc, s91, v12
	s_nop 1
	v_cndmask_b32_e32 v12, v229, v13, vcc
	v_sub_f32_e32 v13, v14, v4
	v_mul_f32_e32 v14, 0x3fb8aa3b, v13
	v_fma_f32 v16, v13, s61, -v14
	v_rndne_f32_e32 v17, v14
	v_fmac_f32_e32 v16, 0x32a5705f, v13
	v_sub_f32_e32 v14, v14, v17
	v_add_f32_e32 v14, v14, v16
	v_exp_f32_e32 v14, v14
	v_cvt_i32_f32_e32 v16, v17
	v_cmp_ngt_f32_e32 vcc, s90, v13
	v_add_f32_e32 v9, v12, v9
	v_ldexp_f32 v14, v14, v16
	v_cndmask_b32_e32 v14, 0, v14, vcc
	v_cmp_nlt_f32_e32 vcc, s91, v13
; DEVI void phase_p7(const int TIDX, const int BIDX, const int GDIM, KAP KA, unsigned char* WSB, float* OUTB, int l, unsigned char* smem) {
;     ...
;         const float gtop = 1.f / gs;
;         float el[8];
; #pragma unroll
;         for (int j = 0; j < 8; ++j) el[j] = __shfl(mine[t], 4 + gi * 8 + j);
;         float em = el[0];
; #pragma unroll
;         for (int j = 1; j < 8; ++j) em = fmaxf(em, el[j]);
;         float pe[8], es = 0.f;
; #pragma unroll
;         for (int j = 0; j < 8; ++j) { pe[j] = expf(el[j] - em); es += pe[j]; }
; #pragma unroll
;         for (int j = 0; j < 8; ++j) pe[j] = pe[j] / es;
;         int i1 = 0; float p1 = pe[0];
; #pragma unroll
;         for (int j = 1; j < 8; ++j) if (pe[j] > p1) { p1 = pe[j]; i1 = j; }
;         int i2 = -1; float p2 = -1.f;
; #pragma unroll
;         for (int j = 0; j < 8; ++j) if (j != i1 && pe[j] > p2) { p2 = pe[j]; i2 = j; }
;         const float den = p1 + p2;
;         if (lane == 2 * t) { my_e = gi * 8 + i1; my_w = gtop * (p1 / den); my_tk = tok * 2; }
;         if (lane == 2 * t + 1) { my_e = gi * 8 + i2; my_w = gtop * (p2 / den); my_tk = tok * 2 + 1; }
	s_nop 1
	v_cndmask_b32_e32 v13, v229, v14, vcc
	v_sub_f32_e32 v14, v15, v4
	v_mul_f32_e32 v15, 0x3fb8aa3b, v14
	v_fma_f32 v16, v14, s61, -v15
	v_rndne_f32_e32 v17, v15
	v_fmac_f32_e32 v16, 0x32a5705f, v14
	v_sub_f32_e32 v15, v15, v17
	v_add_f32_e32 v15, v15, v16
	v_exp_f32_e32 v15, v15
	v_cvt_i32_f32_e32 v16, v17
	v_cmp_ngt_f32_e32 vcc, s90, v14
	v_sub_f32_e32 v4, v8, v4
	v_mul_f32_e32 v8, 0x3fb8aa3b, v4
	v_ldexp_f32 v15, v15, v16
	v_cndmask_b32_e32 v15, 0, v15, vcc
	v_cmp_nlt_f32_e32 vcc, s91, v14
	v_rndne_f32_e32 v16, v8
	v_add_f32_e32 v9, v13, v9
	v_cndmask_b32_e32 v14, v229, v15, vcc
	v_fma_f32 v15, v4, s61, -v8
	v_fmac_f32_e32 v15, 0x32a5705f, v4
	v_sub_f32_e32 v8, v8, v16
	v_add_f32_e32 v8, v8, v15
	v_exp_f32_e32 v8, v8
	v_cvt_i32_f32_e32 v15, v16
	v_cmp_ngt_f32_e32 vcc, s90, v4
	v_add_f32_e32 v9, v14, v9
	v_ldexp_f32 v8, v8, v15
	v_cndmask_b32_e32 v8, 0, v8, vcc
	v_cmp_nlt_f32_e32 vcc, s91, v4
	s_nop 1
	v_cndmask_b32_e32 v4, v229, v8, vcc
	v_add_f32_e32 v8, v4, v9
	v_div_scale_f32 v9, s[0:1], v8, v8, v6
	v_rcp_f32_e32 v15, v9
	s_nop 0
	v_fma_f32 v16, -v9, v15, 1.0
	v_fmac_f32_e32 v15, v16, v15
	v_div_scale_f32 v16, vcc, v6, v8, v6
	v_mul_f32_e32 v17, v16, v15
	v_fma_f32 v18, -v9, v17, v16
	v_fmac_f32_e32 v17, v18, v15
	v_fma_f32 v9, -v9, v17, v16
	v_div_fmas_f32 v9, v9, v15, v17
	v_div_fixup_f32 v6, v9, v8, v6
	v_div_scale_f32 v9, s[0:1], v8, v8, v7
	v_rcp_f32_e32 v15, v9
	v_cmp_nlt_f32_e64 s[24:25], -1.0, v6
	v_fma_f32 v16, -v9, v15, 1.0
	v_fmac_f32_e32 v15, v16, v15
	v_div_scale_f32 v16, vcc, v7, v8, v7
	v_mul_f32_e32 v17, v16, v15
	v_fma_f32 v18, -v9, v17, v16
	v_fmac_f32_e32 v17, v18, v15
	v_fma_f32 v9, -v9, v17, v16
	v_div_fmas_f32 v9, v9, v15, v17
	v_div_fixup_f32 v9, v9, v8, v7
	v_div_scale_f32 v7, s[0:1], v8, v8, v10
	v_rcp_f32_e32 v15, v7
	s_nop 0
	v_fma_f32 v16, -v7, v15, 1.0
	v_fmac_f32_e32 v15, v16, v15
	v_div_scale_f32 v16, vcc, v10, v8, v10
	v_mul_f32_e32 v17, v16, v15
	v_fma_f32 v18, -v7, v17, v16
	v_fmac_f32_e32 v17, v18, v15
	v_fma_f32 v7, -v7, v17, v16
	v_div_fmas_f32 v7, v7, v15, v17
	v_div_fixup_f32 v10, v7, v8, v10
	v_div_scale_f32 v7, s[0:1], v8, v8, v11
	v_rcp_f32_e32 v15, v7
	s_nop 0
	v_fma_f32 v16, -v7, v15, 1.0
	v_fmac_f32_e32 v15, v16, v15
	v_div_scale_f32 v16, vcc, v11, v8, v11
	v_mul_f32_e32 v17, v16, v15
	v_fma_f32 v18, -v7, v17, v16
	v_fmac_f32_e32 v17, v18, v15
	v_fma_f32 v7, -v7, v17, v16
	v_div_fmas_f32 v7, v7, v15, v17
	v_div_fixup_f32 v11, v7, v8, v11
	v_div_scale_f32 v7, s[0:1], v8, v8, v12
	v_rcp_f32_e32 v15, v7
	s_nop 0
	v_fma_f32 v16, -v7, v15, 1.0
	v_fmac_f32_e32 v15, v16, v15
	v_div_scale_f32 v16, vcc, v12, v8, v12
	v_mul_f32_e32 v17, v16, v15
	v_fma_f32 v18, -v7, v17, v16
	v_fmac_f32_e32 v17, v18, v15
	v_fma_f32 v7, -v7, v17, v16
	v_div_fmas_f32 v7, v7, v15, v17
	v_div_fixup_f32 v12, v7, v8, v12
	v_div_scale_f32 v7, s[0:1], v8, v8, v13
	v_rcp_f32_e32 v15, v7
	s_nop 0
	v_fma_f32 v16, -v7, v15, 1.0
	v_fmac_f32_e32 v15, v16, v15
	v_div_scale_f32 v16, vcc, v13, v8, v13
	v_mul_f32_e32 v17, v16, v15
	v_fma_f32 v18, -v7, v17, v16
	v_fmac_f32_e32 v17, v18, v15
	v_fma_f32 v7, -v7, v17, v16
	v_div_fmas_f32 v7, v7, v15, v17
	v_div_fixup_f32 v13, v7, v8, v13
	v_div_scale_f32 v7, s[0:1], v8, v8, v14
	v_rcp_f32_e32 v15, v7
	s_nop 0
	v_fma_f32 v16, -v7, v15, 1.0
	v_fmac_f32_e32 v15, v16, v15
	v_div_scale_f32 v16, vcc, v14, v8, v14
	v_mul_f32_e32 v17, v16, v15
	v_fma_f32 v18, -v7, v17, v16
	v_fmac_f32_e32 v17, v18, v15
	v_fma_f32 v7, -v7, v17, v16
	v_div_fmas_f32 v7, v7, v15, v17
	v_div_fixup_f32 v14, v7, v8, v14
	v_div_scale_f32 v7, s[0:1], v8, v8, v4
	v_rcp_f32_e32 v15, v7
	s_nop 0
	v_fma_f32 v16, -v7, v15, 1.0
	v_fmac_f32_e32 v15, v16, v15
	v_div_scale_f32 v16, vcc, v4, v8, v4
	v_mul_f32_e32 v17, v16, v15
	v_fma_f32 v18, -v7, v17, v16
	v_fmac_f32_e32 v17, v18, v15
	v_fma_f32 v7, -v7, v17, v16
	v_div_fmas_f32 v7, v7, v15, v17
	v_cmp_gt_f32_e32 vcc, v9, v6
	v_div_fixup_f32 v4, v7, v8, v4
	s_nop 0
	v_cndmask_b32_e32 v8, v6, v9, vcc
	v_cndmask_b32_e64 v7, 0, 1, vcc
	v_cmp_gt_f32_e32 vcc, v10, v8
	s_nop 1
	v_cndmask_b32_e32 v8, v8, v10, vcc
	v_cndmask_b32_e64 v7, v7, 2, vcc
	v_cmp_gt_f32_e32 vcc, v11, v8
	s_nop 1
	v_cndmask_b32_e32 v8, v8, v11, vcc
	v_cndmask_b32_e64 v7, v7, 3, vcc
	v_cmp_gt_f32_e32 vcc, v12, v8
	s_nop 1
	v_cndmask_b32_e32 v8, v8, v12, vcc
	v_cndmask_b32_e64 v7, v7, 4, vcc
	v_cmp_gt_f32_e32 vcc, v13, v8
	s_nop 1
	v_cndmask_b32_e32 v8, v8, v13, vcc
	v_cndmask_b32_e64 v7, v7, 5, vcc
	v_cmp_gt_f32_e32 vcc, v14, v8
	s_nop 1
	v_cndmask_b32_e32 v15, v8, v14, vcc
	v_cndmask_b32_e64 v7, v7, 6, vcc
	v_cmp_ngt_f32_e64 s[36:37], v4, v15
	s_and_b64 s[2:3], vcc, s[36:37]
	s_nop 0
	v_cndmask_b32_e64 v8, 7, v7, s[36:37]
	v_cmp_eq_u32_e64 s[22:23], 0, v8
	s_or_b64 s[0:1], s[24:25], s[22:23]
	v_cndmask_b32_e64 v6, v6, -1.0, s[0:1]
	v_cmp_ne_u32_e64 s[22:23], 1, v8
	v_cmp_gt_f32_e64 s[24:25], v9, v6
	s_and_b64 s[22:23], s[22:23], s[24:25]
	v_cndmask_b32_e64 v6, v6, v9, s[22:23]
	v_cmp_ne_u32_e64 s[24:25], 2, v8
	v_cmp_gt_f32_e64 s[26:27], v10, v6
	s_and_b64 s[24:25], s[24:25], s[26:27]
	v_cndmask_b32_e64 v6, v6, v10, s[24:25]
	v_cmp_ne_u32_e64 s[26:27], 3, v8
	v_cmp_gt_f32_e64 s[28:29], v11, v6
	s_and_b64 s[26:27], s[26:27], s[28:29]
	v_cndmask_b32_e64 v6, v6, v11, s[26:27]
	v_cmp_ne_u32_e64 s[28:29], 4, v8
	v_cmp_gt_f32_e64 s[30:31], v12, v6
	s_and_b64 s[28:29], s[28:29], s[30:31]
	v_cndmask_b32_e64 v6, v6, v12, s[28:29]
	v_cmp_ne_u32_e64 s[30:31], 5, v8
	v_cmp_gt_f32_e64 s[34:35], v13, v6
	s_and_b64 s[34:35], s[30:31], s[34:35]
	v_cndmask_b32_e64 v7, v4, v15, s[36:37]
	v_cndmask_b32_e64 v6, v6, v13, s[34:35]
	v_cmp_ngt_f32_e32 vcc, v14, v6
	s_or_b64 s[30:31], s[2:3], vcc
	v_cndmask_b32_e64 v6, v14, v6, s[30:31]
	v_cmp_gt_f32_e32 vcc, v4, v6
	s_and_b64 s[36:37], s[36:37], vcc
	v_cndmask_b32_e64 v6, v6, v4, s[36:37]
	v_div_scale_f32 v4, s[2:3], v3, v3, 1.0
	v_rcp_f32_e32 v9, v4
	s_nop 0
	v_fma_f32 v10, -v4, v9, 1.0
	v_fmac_f32_e32 v9, v10, v9
	v_div_scale_f32 v10, vcc, 1.0, v3, 1.0
	v_mul_f32_e32 v11, v10, v9
	v_fma_f32 v12, -v4, v11, v10
	v_fmac_f32_e32 v11, v12, v9
	v_fma_f32 v4, -v4, v11, v10
	v_div_fmas_f32 v4, v4, v9, v11
	v_div_fixup_f32 v9, v4, v3, 1.0
	v_add_f32_e32 v10, v7, v6
	v_mov_b32_e32 v4, 0
	v_mov_b32_e32 v3, 0
	s_and_saveexec_b64 s[2:3], s[6:7]
	s_cbranch_execz .LBB0_72
	v_div_scale_f32 v2, s[62:63], v10, v10, v7
	v_rcp_f32_e32 v4, v2
	v_add_u32_e32 v3, v8, v5
	v_fma_f32 v8, -v2, v4, 1.0
	v_fmac_f32_e32 v4, v8, v4
	v_div_scale_f32 v8, vcc, v7, v10, v7
	v_mul_f32_e32 v11, v8, v4
	v_fma_f32 v12, -v2, v11, v8
	v_fmac_f32_e32 v11, v12, v4
	v_fma_f32 v2, -v2, v11, v8
	v_div_fmas_f32 v2, v2, v4, v11
	v_div_fixup_f32 v2, v2, v10, v7
	v_mul_f32_e32 v4, v9, v2
	v_lshlrev_b32_e32 v2, 3, v32
